# P5 rstd-fill loads and P4 tail/sample-row loads issued earlier (merged with tail load hoist)
# baseline (speedup 1.0000x reference)
; #define LAS __attribute__((address_space(3)))
; __device__ __forceinline__ unsigned pk2(float lo, float hi) { return f2bf(lo) | (f2bf(hi) << 16); }
; #define PHASE_IDS() const int tid = fresh_tid(), lane = tid & 63, wave = __builtin_amdgcn_readfirstlane(tid >> 6), gw = bx * NWAVES + wave; (void)lane; (void)gw
; __global__ void __launch_bounds__(NWAVES * 64, 2) fwd_megakernel(Args args) {
;     ...
;         PHASE_IDS();
;         for (int m0 = gw * 4; m0 < MP; m0 += NGW * 4) {
;             f32x4 v[4];
; #pragma unroll
;             for (int q = 0; q < 4; ++q) v[q] = __builtin_nontemporal_load((const f32x4*)(p_prompt + (size_t)(m0 + q) * 256) + lane);
; #pragma unroll
;             for (int q = 0; q < 4; ++q) { u32x2 w; w.x = pk2(v[q][0], v[q][1]); w.y = pk2(v[q][2], v[q][3]); *((u32x2*)(HP + (size_t)(m0 + q) * LDHP + 1024) + lane) = w; }
;         }
;         for (int m = MP + gw; m < M; m += NGW) {
;             const f32x4 v = *((const f32x4*)(p_sample + (size_t)(m - MP) * 256) + lane);
;     ...
;             const int tm = bx >> 4, tn = bx & 15, row0 = MP + 32 * tm, col0 = 64 * tn, kw = wave * 128;
;             LAS float* parts = (LAS float*)lds;
;             tail_partial<4>(R1 + (size_t)row0 * DM + kw, DM, Wout_t + kw, DM, col0, parts + wave * 2048, lane);
.LBB0_878:
	s_or_b64 exec, exec, s[0:1]
	s_waitcnt lgkmcnt(0)
	v_mov_b32_e32 v1, v0
	s_barrier
	s_nop 0
	v_readfirstlane_b32 s0, v1
	s_ashr_i32 s2, s0, 6
	v_readlane_b32 s0, v254, 6
	v_and_b32_e32 v2, 63, v1
	s_add_i32 s3, s2, s0
	v_lshlrev_b32_e32 v4, 3, v2
	v_lshlrev_b32_e32 v2, 4, v2
	s_cmpk_gt_i32 s3, 0x1ff
	s_cbranch_scc1 .Lp4s_skip
	s_lshl_b32 s12, s3, 10
	s_add_u32 s12, s78, s12
	s_addc_u32 s13, s79, 0
	global_load_dwordx4 v[240:243], v2, s[12:13]
.Lp4s_skip:
	v_readlane_b32 s12, v254, 19
	v_readlane_b32 s13, v254, 20
	s_and_b64 vcc, exec, s[12:13]
	s_cbranch_vccz .Lp4t_skip
	s_ashr_i32 s85, s84, 31
	s_and_b32 s11, s94, 15
	s_lshl_b32 s12, s11, 6
	s_lshl_b64 s[14:15], s[84:85], 11
	s_add_u32 s11, s80, s14
	s_addc_u32 s13, s81, s15
	s_lshl_b32 s14, s94, 5
	s_and_b32 s15, s14, 0x60
	s_lshl_b32 s16, s2, 7
	s_ashr_i32 s17, s16, 31
	s_lshl_b64 s[18:19], s[16:17], 1
	s_add_u32 s16, s11, s18
	s_addc_u32 s17, s13, s19
	s_add_u32 s26, s96, s18
	v_and_b32_e32 v86, 15, v1
	v_mov_b32_e32 v89, 0
	s_addc_u32 s27, s97, s19
	s_and_b32 s11, s12, 0x300
	v_lshlrev_b32_e32 v90, 11, v86
	v_mov_b32_e32 v91, v89
	v_and_b32_e32 v88, 48, v1
	s_or_b32 s13, s11, s15
	v_lshl_add_u64 v[92:93], s[16:17], 0, v[90:91]
	v_or_b32_e32 v87, s13, v86
	v_lshl_add_u64 v[90:91], v[92:93], 0, v[88:89]
	s_mov_b32 s11, 0x8000
	v_lshl_add_u64 v[92:93], s[26:27], 0, v[88:89]
	v_lshlrev_b32_e32 v94, 11, v87
	v_mov_b32_e32 v95, v89
	v_add_co_u32_e32 v96, vcc, s11, v90
	s_nop 1
	v_lshl_add_u64 v[98:99], v[92:93], 0, v[94:95]
	v_addc_co_u32_e32 v97, vcc, 0, v91, vcc
	s_nop 1
	v_add_co_u32_e32 v92, vcc, s11, v98
	s_nop 1
	s_mov_b32 s11, 0x40000
	v_addc_co_u32_e32 v93, vcc, 0, v99, vcc
	s_nop 1
	v_add_co_u32_e32 v94, vcc, s11, v98
	s_nop 1
	global_load_dwordx4 v[100:103], v[98:99], off
	global_load_dwordx4 v[104:107], v[98:99], off offset:64
	v_addc_co_u32_e32 v95, vcc, 0, v99, vcc
	s_nop 1
	global_load_dwordx4 v[108:111], v[96:97], off
	global_load_dwordx4 v[112:115], v[92:93], off
	global_load_dwordx4 v[116:119], v[94:95], off
	s_mov_b32 s11, 0x48000
	v_add_co_u32_e32 v120, vcc, s11, v98
	s_nop 1
	global_load_dwordx4 v[124:127], v[90:91], off
	global_load_dwordx4 v[128:131], v[90:91], off offset:64
	v_addc_co_u32_e32 v121, vcc, 0, v99, vcc
	s_nop 1
	global_load_dwordx4 v[132:135], v[120:121], off
	global_load_dwordx4 v[136:139], v[96:97], off offset:64
	global_load_dwordx4 v[140:143], v[92:93], off offset:64
	global_load_dwordx4 v[144:147], v[94:95], off offset:64
	global_load_dwordx4 v[148:151], v[120:121], off offset:64
	global_load_dwordx4 v[152:155], v[98:99], off offset:128
	global_load_dwordx4 v[156:159], v[90:91], off offset:128
	global_load_dwordx4 v[160:163], v[96:97], off offset:128
	global_load_dwordx4 v[164:167], v[92:93], off offset:128
	global_load_dwordx4 v[168:171], v[94:95], off offset:128
	global_load_dwordx4 v[172:175], v[90:91], off offset:192
	global_load_dwordx4 v[176:179], v[98:99], off offset:192
	global_load_dwordx4 v[180:183], v[120:121], off offset:128
	global_load_dwordx4 v[184:187], v[96:97], off offset:192
	global_load_dwordx4 v[96:99], v[120:121], off offset:192
	global_load_dwordx4 v[120:123], v[92:93], off offset:192
	global_load_dwordx4 v[188:191], v[94:95], off offset:192
	v_lshl_or_b32 v87, v86, 2, s12
	v_ashrrev_i32_e32 v86, 4, v1
	v_add_u32_e32 v90, s92, v86
	v_ashrrev_i32_e32 v91, 31, v90
	v_lshlrev_b64 v[92:93], 12, v[90:91]
	v_lshl_add_u64 v[90:91], s[66:67], 0, v[92:93]
	v_lshlrev_b32_e32 v86, 2, v87
	v_mov_b32_e32 v92, v86
	v_mov_b32_e32 v93, v89
	v_lshl_add_u64 v[94:95], v[90:91], 0, v[92:93]
	global_load_dwordx4 v[88:91], v[94:95], off
; __device__ __forceinline__ unsigned pk2(float lo, float hi) { return f2bf(lo) | (f2bf(hi) << 16); }
; __global__ void __launch_bounds__(NWAVES * 64, 2) fwd_megakernel(Args args) {
;     ...
;         for (int m0 = gw * 4; m0 < MP; m0 += NGW * 4) {
;             f32x4 v[4];
; #pragma unroll
;             for (int q = 0; q < 4; ++q) v[q] = __builtin_nontemporal_load((const f32x4*)(p_prompt + (size_t)(m0 + q) * 256) + lane);
; #pragma unroll
;             for (int q = 0; q < 4; ++q) { u32x2 w; w.x = pk2(v[q][0], v[q][1]); w.y = pk2(v[q][2], v[q][3]); *((u32x2*)(HP + (size_t)(m0 + q) * LDHP + 1024) + lane) = w; }
;         }
.Lp4t_skip:
	s_cmpk_gt_i32 s3, 0x1fff
	s_cbranch_scc1 .LBB0_881
	s_lshl_b32 s4, s3, 2
	s_lshl_b32 s0, s93, 5
	s_ashr_i32 s5, s4, 31
	s_mul_i32 s1, s3, 0x2800
	s_mul_hi_i32 s7, s4, 0xa00
	s_add_u32 s6, s62, s1
	s_addc_u32 s7, s63, s7
	s_ashr_i32 s1, s0, 31
	s_lshl_b64 s[8:9], s[4:5], 10
	v_mov_b32_e32 v5, 0
	s_add_u32 s8, s76, s8
	v_mov_b32_e32 v3, v5
	s_addc_u32 s9, s77, s9
	v_lshl_add_u64 v[6:7], s[6:7], 0, v[4:5]
	s_mov_b64 s[6:7], 0x5a00800
	v_lshl_add_u64 v[8:9], s[8:9], 0, v[2:3]
	s_mov_b64 s[8:9], 0xc00
	v_lshl_add_u64 v[6:7], v[6:7], 0, s[6:7]
	s_mul_i32 s6, s93, 0x14000
	s_mul_hi_i32 s7, s0, 0xa00
	v_lshl_add_u64 v[8:9], v[8:9], 0, s[8:9]
	s_lshl_b64 s[8:9], s[0:1], 10
	s_movk_i32 s1, 0x7fff
	s_mov_b32 s5, 0xffff0000
	s_movk_i32 s10, 0x1000
	s_mul_i32 s11, s0, 3
	s_add_i32 s11, s11, s4
	s_cmp_lt_i32 s11, 0x8000
	s_mov_b32 s11, 0
	s_cbranch_scc0 .LBB0_880
	v_lshl_add_u64 v[74:75], v[8:9], 0, s[8:9]
	v_lshl_add_u64 v[76:77], v[74:75], 0, s[8:9]
	v_lshl_add_u64 v[78:79], v[76:77], 0, s[8:9]
	global_load_dwordx4 v[10:13], v[8:9], off offset:-3072 nt
	global_load_dwordx4 v[14:17], v[8:9], off offset:-2048 nt
	global_load_dwordx4 v[18:21], v[8:9], off offset:-1024 nt
	global_load_dwordx4 v[22:25], v[8:9], off nt
	global_load_dwordx4 v[26:29], v[74:75], off offset:-3072 nt
	global_load_dwordx4 v[30:33], v[74:75], off offset:-2048 nt
	global_load_dwordx4 v[34:37], v[74:75], off offset:-1024 nt
	global_load_dwordx4 v[38:41], v[74:75], off nt
	global_load_dwordx4 v[42:45], v[76:77], off offset:-3072 nt
	global_load_dwordx4 v[46:49], v[76:77], off offset:-2048 nt
	global_load_dwordx4 v[50:53], v[76:77], off offset:-1024 nt
	global_load_dwordx4 v[54:57], v[76:77], off nt
	global_load_dwordx4 v[58:61], v[78:79], off offset:-3072 nt
	global_load_dwordx4 v[62:65], v[78:79], off offset:-2048 nt
	global_load_dwordx4 v[66:69], v[78:79], off offset:-1024 nt
	global_load_dwordx4 v[70:73], v[78:79], off nt
	v_lshl_add_u64 v[80:81], v[6:7], 0, s[10:11]
	s_waitcnt vmcnt(15)
	v_cvt_pk_bf16_f32 v82, v10, v11
	v_cvt_pk_bf16_f32 v83, v12, v13
	global_store_dwordx2 v[6:7], v[82:83], off
	s_waitcnt vmcnt(15)
	v_cvt_pk_bf16_f32 v84, v14, v15
	v_cvt_pk_bf16_f32 v85, v16, v17
	global_store_dwordx2 v[6:7], v[84:85], off offset:2560
	s_waitcnt vmcnt(15)
	v_cvt_pk_bf16_f32 v82, v18, v19
	v_cvt_pk_bf16_f32 v83, v20, v21
	global_store_dwordx2 v[80:81], v[82:83], off offset:1024
	s_waitcnt vmcnt(15)
	v_cvt_pk_bf16_f32 v84, v22, v23
	v_cvt_pk_bf16_f32 v85, v24, v25
	global_store_dwordx2 v[80:81], v[84:85], off offset:3584
	v_lshl_add_u64 v[6:7], v[6:7], 0, s[6:7]
	v_lshl_add_u64 v[80:81], v[6:7], 0, s[10:11]
	s_waitcnt vmcnt(15)
	v_cvt_pk_bf16_f32 v82, v26, v27
	v_cvt_pk_bf16_f32 v83, v28, v29
	global_store_dwordx2 v[6:7], v[82:83], off
	s_waitcnt vmcnt(15)
	v_cvt_pk_bf16_f32 v84, v30, v31
	v_cvt_pk_bf16_f32 v85, v32, v33
	global_store_dwordx2 v[6:7], v[84:85], off offset:2560
	s_waitcnt vmcnt(15)
	v_cvt_pk_bf16_f32 v82, v34, v35
	v_cvt_pk_bf16_f32 v83, v36, v37
	global_store_dwordx2 v[80:81], v[82:83], off offset:1024
	s_waitcnt vmcnt(15)
	v_cvt_pk_bf16_f32 v84, v38, v39
	v_cvt_pk_bf16_f32 v85, v40, v41
	global_store_dwordx2 v[80:81], v[84:85], off offset:3584
	v_lshl_add_u64 v[6:7], v[6:7], 0, s[6:7]
	v_lshl_add_u64 v[80:81], v[6:7], 0, s[10:11]
	s_waitcnt vmcnt(15)
	v_cvt_pk_bf16_f32 v82, v42, v43
	v_cvt_pk_bf16_f32 v83, v44, v45
	global_store_dwordx2 v[6:7], v[82:83], off
	s_waitcnt vmcnt(15)
	v_cvt_pk_bf16_f32 v84, v46, v47
	v_cvt_pk_bf16_f32 v85, v48, v49
	global_store_dwordx2 v[6:7], v[84:85], off offset:2560
	s_waitcnt vmcnt(15)
	v_cvt_pk_bf16_f32 v82, v50, v51
	v_cvt_pk_bf16_f32 v83, v52, v53
	global_store_dwordx2 v[80:81], v[82:83], off offset:1024
	s_waitcnt vmcnt(15)
	v_cvt_pk_bf16_f32 v84, v54, v55
	v_cvt_pk_bf16_f32 v85, v56, v57
	global_store_dwordx2 v[80:81], v[84:85], off offset:3584
	v_lshl_add_u64 v[6:7], v[6:7], 0, s[6:7]
	v_lshl_add_u64 v[80:81], v[6:7], 0, s[10:11]
	s_waitcnt vmcnt(15)
	v_cvt_pk_bf16_f32 v82, v58, v59
	v_cvt_pk_bf16_f32 v83, v60, v61
	global_store_dwordx2 v[6:7], v[82:83], off
	s_waitcnt vmcnt(15)
	v_cvt_pk_bf16_f32 v84, v62, v63
	v_cvt_pk_bf16_f32 v85, v64, v65
	global_store_dwordx2 v[6:7], v[84:85], off offset:2560
	s_waitcnt vmcnt(15)
	v_cvt_pk_bf16_f32 v82, v66, v67
	v_cvt_pk_bf16_f32 v83, v68, v69
	global_store_dwordx2 v[80:81], v[82:83], off offset:1024
	s_waitcnt vmcnt(15)
	v_cvt_pk_bf16_f32 v84, v70, v71
	v_cvt_pk_bf16_f32 v85, v72, v73
	global_store_dwordx2 v[80:81], v[84:85], off offset:3584
	s_branch .LBB0_881

; #define LAS __attribute__((address_space(3)))
; __device__ __forceinline__ unsigned pk2(float lo, float hi) { return f2bf(lo) | (f2bf(hi) << 16); }
; __device__ __forceinline__ int permrow(int n) { return (n & ~255) | ((((n >> 5) & 1) * 128) + (((n >> 6) & 3) * 32) + (n & 31)); }
; template <int KSTEPS>
; __device__ __forceinline__ void tail_partial(const bf16_t* A, int lda, const bf16_t* Bt, int ldb, int col0, LAS float* part, int lane) {
;     ...
;     const bf16_t* ap = A + (size_t)fr * lda + 8 * fq;
;     const bf16_t* bp[4];
; #pragma unroll
;     for (int n = 0; n < 4; ++n) bp[n] = Bt + (size_t)permrow(col0 + 16 * n + fr) * ldb + 8 * fq;
; #pragma unroll
;     for (int ks = 0; ks < KSTEPS; ++ks) {
;         bf16x8 a[2], b[4];
; #pragma unroll
;         for (int m = 0; m < 2; ++m) a[m] = *(const bf16x8*)(ap + (size_t)(16 * m) * lda + 32 * ks);
; #pragma unroll
;         for (int n = 0; n < 4; ++n) b[n] = *(const bf16x8*)(bp[n] + 32 * ks);
; __global__ void __launch_bounds__(NWAVES * 64, 2) fwd_megakernel(Args args) {
;     ...
;         for (int m = MP + gw; m < M; m += NGW) {
;             const f32x4 v = *((const f32x4*)(p_sample + (size_t)(m - MP) * 256) + lane);
;             u32x2 w; w.x = pk2(v[0], v[1]); w.y = pk2(v[2], v[3]);
;             *((u32x2*)(HP + (size_t)m * LDHP + 1024) + lane) = w;
;         }
;         if (G == 256) {
;             const int tm = bx >> 4, tn = bx & 15, row0 = MP + 32 * tm, col0 = 64 * tn, kw = wave * 128;
;             LAS float* parts = (LAS float*)lds;
;             tail_partial<4>(R1 + (size_t)row0 * DM + kw, DM, Wout_t + kw, DM, col0, parts + wave * 2048, lane);
.LBB0_881:
	s_cmpk_gt_i32 s3, 0x1ff
	v_readlane_b32 s8, v254, 7
	v_readlane_b32 s9, v254, 8
	s_cbranch_scc1 .LBB0_884
	s_add_i32 s3, s3, 0x8000
	s_mul_i32 s0, s3, 0xa00
	s_mul_hi_i32 s1, s3, 0xa00
	s_add_u32 s0, s62, s0
	v_readlane_b32 s4, v254, 6
	s_addc_u32 s1, s63, s1
	s_ashr_i32 s9, s8, 31
	s_ashr_i32 s5, s2, 31
	s_ashr_i32 s6, s4, 31
	s_add_u32 s4, s2, s4
	s_addc_u32 s5, s5, s6
	s_lshl_b64 s[4:5], s[4:5], 10
	v_mov_b32_e32 v5, 0
	s_add_u32 s4, s78, s4
	v_lshl_add_u64 v[6:7], s[0:1], 0, v[4:5]
	s_mov_b64 s[0:1], 0x5a00800
	v_mov_b32_e32 v3, v5
	s_addc_u32 s5, s79, s5
	v_lshl_add_u64 v[6:7], v[6:7], 0, s[0:1]
	s_mul_hi_i32 s1, s8, 0xa00
	s_mul_i32 s0, s8, 0xa00
	v_lshl_add_u64 v[2:3], s[4:5], 0, v[2:3]
	s_lshl_b64 s[4:5], s[8:9], 10
	s_movk_i32 s6, 0x7fff
	s_mov_b32 s7, 0xffff0000
	s_waitcnt vmcnt(0)
	v_mov_b32_e32 v8, v240
	v_mov_b32_e32 v9, v241
	v_mov_b32_e32 v10, v242
	v_mov_b32_e32 v11, v243
	s_branch .Lp4s_have
.LBB0_883:
	global_load_dwordx4 v[8:11], v[2:3], off
	s_waitcnt vmcnt(0)
.Lp4s_have:
	s_add_i32 s3, s3, s8
	v_lshl_add_u64 v[2:3], v[2:3], 0, s[4:5]
	s_cmp_gt_i32 s3, 0x81ff
	v_bfe_u32 v4, v8, 16, 1
	v_bfe_u32 v12, v10, 16, 1
	v_bfe_u32 v5, v9, 16, 1
	v_bfe_u32 v13, v11, 16, 1
	v_add3_u32 v4, v8, v4, s6
	v_add3_u32 v8, v10, v12, s6
	v_add3_u32 v5, v9, v5, s6
	v_add3_u32 v9, v11, v13, s6
	v_lshrrev_b32_e32 v4, 16, v4
	v_lshrrev_b32_e32 v8, 16, v8
	v_and_or_b32 v4, v5, s7, v4
	v_and_or_b32 v5, v9, s7, v8
	global_store_dwordx2 v[6:7], v[4:5], off
	v_lshl_add_u64 v[6:7], v[6:7], 0, s[0:1]
	s_cbranch_scc0 .LBB0_883
.LBB0_884:
	v_readlane_b32 s0, v254, 19
	s_add_u32 s8, s62, 0x1400000
	v_readlane_b32 s1, v254, 20
	s_addc_u32 s9, s63, 0
	s_ashr_i32 s85, s84, 31
	s_movk_i32 s24, 0x82
	s_and_b64 vcc, exec, s[0:1]
	s_cbranch_vccz .LBB0_888
	s_and_b32 s3, s94, 15
	s_lshl_b32 s0, s3, 6
	s_lshl_b64 s[4:5], s[84:85], 11
	s_add_u32 s1, s80, s4
	s_addc_u32 s7, s81, s5
	s_lshl_b32 s4, s94, 5
	s_and_b32 s10, s4, 0x60
	s_lshl_b32 s4, s2, 7
	s_ashr_i32 s5, s4, 31
	s_lshl_b64 s[4:5], s[4:5], 1
	s_add_u32 s6, s1, s4
	s_addc_u32 s7, s7, s5
	s_add_u32 s4, s96, s4
	v_and_b32_e32 v80, 15, v1
	v_mov_b32_e32 v3, 0
	s_addc_u32 s5, s97, s5
	s_and_b32 s1, s0, 0x300
	v_lshlrev_b32_e32 v8, 11, v80
	v_mov_b32_e32 v9, v3
	v_and_b32_e32 v2, 48, v1
	s_or_b32 s1, s1, s10
	v_lshl_add_u64 v[8:9], s[6:7], 0, v[8:9]
	v_or_b32_e32 v6, s1, v80
	v_lshl_add_u64 v[66:67], v[8:9], 0, v[2:3]
	s_mov_b32 s1, 0x8000
	v_lshl_add_u64 v[4:5], s[4:5], 0, v[2:3]
	v_lshlrev_b32_e32 v6, 11, v6
	v_mov_b32_e32 v7, v3
	v_add_co_u32_e32 v68, vcc, s1, v66
	v_lshl_add_u64 v[64:65], v[4:5], 0, v[6:7]
	s_nop 0
	v_addc_co_u32_e32 v69, vcc, 0, v67, vcc
	v_add_co_u32_e32 v72, vcc, s1, v64
	s_mov_b32 s4, 0x40000
	s_nop 0
	v_addc_co_u32_e32 v73, vcc, 0, v65, vcc
	v_add_co_u32_e32 v74, vcc, s4, v64
	s_nop 0
	s_nop 0
	v_addc_co_u32_e32 v75, vcc, 0, v65, vcc
	s_nop 0
	s_nop 0
	s_nop 0
	s_mov_b32 s1, 0x48000
	v_add_co_u32_e32 v76, vcc, s1, v64
	s_nop 0
	s_nop 0
	v_addc_co_u32_e32 v77, vcc, 0, v65, vcc
	s_nop 0
	s_nop 0
	s_nop 0
	s_nop 0
	s_nop 0
	s_lshl_b32 s1, s2, 13
	s_add_i32 s1, s1, 0
	s_nop 0
	s_waitcnt vmcnt(19)
	v_mfma_f32_16x16x32_bf16 v[32:35], v[100:103], v[124:127], 0
	v_mfma_f32_16x16x32_bf16 v[4:7], v[100:103], v[108:111], 0
	v_mfma_f32_16x16x32_bf16 v[48:51], v[112:115], v[124:127], 0
	v_mfma_f32_16x16x32_bf16 v[56:59], v[116:119], v[124:127], 0
	s_nop 0
	s_waitcnt vmcnt(17)
	v_mfma_f32_16x16x32_bf16 v[8:11], v[132:135], v[124:127], 0
	v_mfma_f32_16x16x32_bf16 v[16:19], v[112:115], v[108:111], 0
	v_mfma_f32_16x16x32_bf16 v[20:23], v[116:119], v[108:111], 0
	v_mfma_f32_16x16x32_bf16 v[12:15], v[132:135], v[108:111], 0
	v_mfma_f32_16x16x32_bf16 v[32:35], v[104:107], v[128:131], v[32:35]
	s_nop 0
	s_waitcnt vmcnt(16)
	v_mfma_f32_16x16x32_bf16 v[4:7], v[104:107], v[136:139], v[4:7]
	s_nop 0
	s_waitcnt vmcnt(15)
	v_mfma_f32_16x16x32_bf16 v[28:31], v[140:143], v[128:131], v[48:51]
	s_nop 0
	s_waitcnt vmcnt(14)
	v_mfma_f32_16x16x32_bf16 v[36:39], v[144:147], v[128:131], v[56:59]
	s_nop 0
	s_waitcnt vmcnt(13)
	v_mfma_f32_16x16x32_bf16 v[8:11], v[148:151], v[128:131], v[8:11]
	s_nop 0
	v_mfma_f32_16x16x32_bf16 v[16:19], v[140:143], v[136:139], v[16:19]
	s_nop 0
	s_nop 0
	v_mfma_f32_16x16x32_bf16 v[20:23], v[144:147], v[136:139], v[20:23]
	s_nop 0
	v_mfma_f32_16x16x32_bf16 v[12:15], v[148:151], v[136:139], v[12:15]
	s_nop 0
	s_nop 0
	s_nop 0
	s_nop 0
	s_nop 0
	s_nop 0
	s_nop 0
	s_nop 0
	s_waitcnt vmcnt(11)
	v_mfma_f32_16x16x32_bf16 v[32:35], v[152:155], v[156:159], v[32:35]
	s_nop 0
	s_nop 0
	s_waitcnt vmcnt(10)
	v_mfma_f32_16x16x32_bf16 v[4:7], v[152:155], v[160:163], v[4:7]
	s_nop 0
	s_nop 0
	s_nop 0
	s_nop 0
	s_waitcnt vmcnt(9)
	v_mfma_f32_16x16x32_bf16 v[28:31], v[164:167], v[156:159], v[28:31]
	s_nop 0
	s_waitcnt vmcnt(8)
	v_mfma_f32_16x16x32_bf16 v[36:39], v[168:171], v[156:159], v[36:39]
	s_nop 0
	s_waitcnt vmcnt(5)
	v_mfma_f32_16x16x32_bf16 v[8:11], v[180:183], v[156:159], v[8:11]
	v_lshl_or_b32 v44, v80, 2, s0
	s_movk_i32 s0, 0xa00
	v_mfma_f32_16x16x32_bf16 v[16:19], v[164:167], v[160:163], v[16:19]
	v_mfma_f32_16x16x32_bf16 v[20:23], v[168:171], v[160:163], v[20:23]
	v_lshlrev_b32_e32 v40, 8, v80
	v_add3_u32 v2, s1, v40, v2
	v_mov_b64_e32 v[42:43], s[82:83]
	v_mfma_f32_16x16x32_bf16 v[32:35], v[176:179], v[172:175], v[32:35]
	s_nop 0
	s_waitcnt vmcnt(2)
	v_mfma_f32_16x16x32_bf16 v[28:31], v[120:123], v[172:175], v[28:31]
	s_nop 5
	ds_write_b128 v2, v[32:35]
	s_nop 0
	s_waitcnt vmcnt(1)
	v_mfma_f32_16x16x32_bf16 v[36:39], v[188:191], v[172:175], v[36:39]
	v_mfma_f32_16x16x32_bf16 v[12:15], v[180:183], v[160:163], v[12:15]
	v_mfma_f32_16x16x32_bf16 v[8:11], v[96:99], v[172:175], v[8:11]
	ds_write_b128 v2, v[28:31] offset:64
	s_nop 4
	ds_write_b128 v2, v[36:39] offset:128
	s_nop 0
	ds_write_b128 v2, v[8:11] offset:192
	v_mfma_f32_16x16x32_bf16 v[4:7], v[176:179], v[184:187], v[4:7]
	v_mfma_f32_16x16x32_bf16 v[16:19], v[120:123], v[184:187], v[16:19]
	v_mfma_f32_16x16x32_bf16 v[8:11], v[188:191], v[184:187], v[20:23]
	s_nop 5
	ds_write_b128 v2, v[4:7] offset:4096
	ds_write_b128 v2, v[16:19] offset:4160
	ds_write_b128 v2, v[8:11] offset:4224
	v_ashrrev_i32_e32 v10, 4, v1
	v_mfma_f32_16x16x32_bf16 v[4:7], v[96:99], v[184:187], v[12:15]
	v_lshl_add_u32 v1, v1, 4, 0
	s_nop 6
	ds_write_b128 v2, v[4:7] offset:4288
	v_add_u32_e32 v4, s92, v10
	v_ashrrev_i32_e32 v5, 31, v4
	v_lshlrev_b64 v[4:5], 12, v[4:5]
	v_lshl_add_u64 v[4:5], s[66:67], 0, v[4:5]
	v_lshlrev_b32_e32 v2, 2, v44
	v_lshl_add_u64 v[4:5], v[4:5], 0, v[2:3]
	s_waitcnt lgkmcnt(0)
	s_barrier
; #define LAS __attribute__((address_space(3)))
; __device__ __forceinline__ unsigned cvt_pk_bf16(float lo, float hi) { const f32x2_t v = {lo, hi}; const bf16x2_t b = __builtin_convertvector(v, bf16x2_t); return __builtin_bit_cast(unsigned, b); }
; __device__ __forceinline__ f32x4 tail_sum(const LAS float* parts, int w0, int w1, int tid) {
;     f32x4 s = (f32x4){0.f, 0.f, 0.f, 0.f};
;     for (int w = w0; w < w1; ++w) s += *(const LAS f32x4*)(parts + w * 2048 + tid * 4);
;     return s;
; __global__ void __launch_bounds__(NWAVES * 64, 2) fwd_megakernel(Args args) {
;     ...
;             __syncthreads();
;             const f32x4 cc = tail_sum(parts, 0, 8, tid);
;             const int r = row0 + (tid >> 4), c = col0 + (tid & 15) * 4;
;             const f32x4 h = cc + *(const f32x4*)(x_sample + (size_t)(r - MP) * DM + c);
;             u32x2 w; w.x = cvt_pk_bf16(h[0], h[1]); w.y = cvt_pk_bf16(h[2], h[3]);
;             *(u32x2*)(HP + (size_t)r * LDHP + c) = w;
;             float ss = (h[0] * h[0] + h[1] * h[1]) + (h[2] * h[2] + h[3] * h[3]);
;             ss += __shfl_xor(ss, 1); ss += __shfl_xor(ss, 2); ss += __shfl_xor(ss, 4); ss += __shfl_xor(ss, 8);
;             if ((tid & 15) == 0) SS[(size_t)r * 16 + tn] = ss;
	s_nop 0
	v_mbcnt_hi_u32_b32 v2, -1, v225
	v_add_u32_e32 v4, s84, v10
	v_and_b32_e32 v10, 64, v2
	v_add_u32_e32 v47, 64, v10
	ds_read_b128 v[10:13], v1
	ds_read_b128 v[14:17], v1 offset:8192
	ds_read_b128 v[18:21], v1 offset:16384
	ds_read_b128 v[22:25], v1 offset:24576
	ds_read_b128 v[26:29], v1 offset:32768
	ds_read_b128 v[30:33], v1 offset:40960
	ds_read_b128 v[34:37], v1 offset:49152
	ds_read_b128 v[38:41], v1 offset:57344
	s_waitcnt lgkmcnt(7)
	v_pk_add_f32 v[12:13], v[12:13], 0 op_sel_hi:[1,0]
	v_pk_add_f32 v[10:11], v[10:11], 0 op_sel_hi:[1,0]
	s_waitcnt lgkmcnt(6)
	v_pk_add_f32 v[12:13], v[12:13], v[16:17]
	v_pk_add_f32 v[10:11], v[10:11], v[14:15]
	s_waitcnt lgkmcnt(5)
	v_pk_add_f32 v[12:13], v[12:13], v[20:21]
	v_pk_add_f32 v[10:11], v[10:11], v[18:19]
	s_waitcnt lgkmcnt(4)
	v_pk_add_f32 v[12:13], v[12:13], v[24:25]
	v_pk_add_f32 v[10:11], v[10:11], v[22:23]
	s_waitcnt lgkmcnt(3)
	v_pk_add_f32 v[12:13], v[12:13], v[28:29]
	v_pk_add_f32 v[10:11], v[10:11], v[26:27]
	s_waitcnt lgkmcnt(2)
	v_pk_add_f32 v[12:13], v[12:13], v[32:33]
	v_pk_add_f32 v[10:11], v[10:11], v[30:31]
	s_waitcnt lgkmcnt(1)
	v_pk_add_f32 v[12:13], v[12:13], v[36:37]
	v_pk_add_f32 v[10:11], v[10:11], v[34:35]
	s_waitcnt lgkmcnt(0)
	v_pk_add_f32 v[12:13], v[12:13], v[40:41]
	v_pk_add_f32 v[10:11], v[10:11], v[38:39]
	v_xor_b32_e32 v5, 1, v2
	v_cmp_lt_i32_e32 vcc, v5, v47
	v_xor_b32_e32 v45, 2, v2
	v_xor_b32_e32 v46, 4, v2
	v_cndmask_b32_e32 v5, v2, v5, vcc
	v_lshlrev_b32_e32 v5, 2, v5
	v_cmp_lt_i32_e32 vcc, v45, v47
	s_nop 0
	s_waitcnt vmcnt(0)
	v_pk_add_f32 v[8:9], v[12:13], v[90:91]
	v_pk_add_f32 v[6:7], v[10:11], v[88:89]
	v_mul_f32_e32 v10, v9, v9
	v_mul_f32_e32 v1, v7, v7
	v_fmac_f32_e32 v1, v6, v6
	v_fmac_f32_e32 v10, v8, v8
	v_add_f32_e32 v1, v1, v10
	ds_bpermute_b32 v5, v5, v1
	v_cndmask_b32_e32 v10, v2, v45, vcc
	v_lshlrev_b32_e32 v10, 2, v10
	v_cmp_lt_i32_e32 vcc, v46, v47
	v_xor_b32_e32 v12, 8, v2
	s_waitcnt lgkmcnt(0)
	v_add_f32_e32 v1, v1, v5
	ds_bpermute_b32 v5, v10, v1
	v_cndmask_b32_e32 v13, v2, v46, vcc
	v_lshlrev_b32_e32 v13, 2, v13
	v_cmp_lt_i32_e32 vcc, v12, v47
	v_mad_i64_i32 v[10:11], s[0:1], v4, s0, v[42:43]
	s_waitcnt lgkmcnt(0)
	v_add_f32_e32 v1, v1, v5
	ds_bpermute_b32 v5, v13, v1
	v_cndmask_b32_e32 v2, v2, v12, vcc
	v_lshlrev_b32_e32 v2, 2, v2
	v_cvt_pk_bf16_f32 v12, v6, v7
	v_cvt_pk_bf16_f32 v13, v8, v9
	s_waitcnt lgkmcnt(0)
	v_add_f32_e32 v1, v1, v5
	ds_bpermute_b32 v6, v2, v1
	v_lshlrev_b32_e32 v2, 1, v44
	v_lshl_add_u64 v[2:3], v[10:11], 0, v[2:3]
	v_cmp_eq_u32_e32 vcc, 0, v80
	global_store_dwordx2 v[2:3], v[12:13], off
	s_and_saveexec_b64 s[0:1], vcc
	s_cbranch_execz .LBB0_887
	s_lshl_b32 s2, s3, 2
	v_ashrrev_i32_e32 v5, 31, v4
	s_add_u32 s2, s8, s2
	s_addc_u32 s3, s9, 0
	v_lshlrev_b64 v[2:3], 6, v[4:5]
	v_lshl_add_u64 v[2:3], s[2:3], 0, v[2:3]
	s_waitcnt lgkmcnt(0)
	v_add_f32_e32 v1, v1, v6
	global_store_dword v[2:3], v1, off

; #define LAS __attribute__((address_space(3)))
; __device__ __forceinline__ int fresh_tid() { int t = threadIdx.x; asm volatile("" : "+v"(t)); return t; }
; #define PHASE_IDS() const int tid = fresh_tid(), lane = tid & 63, wave = __builtin_amdgcn_readfirstlane(tid >> 6), gw = bx * NWAVES + wave; (void)lane; (void)gw
; __global__ void __launch_bounds__(NWAVES * 64, 2) fwd_megakernel(Args args) {
;     ...
;         if (G == 256) {
;             PHASE_IDS();
;             const int tm = bx >> 4, tn = bx & 15, row0 = MP + 32 * tm, col0 = 64 * tn;
;             LAS float* parts = (LAS float*)lds;
;             tail_partial<1>(HP + (size_t)row0 * LDHP + 1024 + wave * 32, LDHP, WGP_t + 1024 + wave * 32, LDHP, col0, parts + wave * 2048, lane);
;             __syncthreads();
;             const f32x4 ple = tail_sum(parts, 0, 8, tid);
;             __syncthreads();
;             tail_partial<4>(HP + (size_t)row0 * LDHP + wave * 128, LDHP, WGP_t + wave * 128, LDHP, col0, parts + wave * 2048, lane);
;     ...
;         if (G == 256) {
;             const int t2 = fresh_tid();
;             rs = (LAS float*)(lds + TBL_OFF);
;             pg8::Unit uu; if (S.next(2 * (t2 >> 8), uu)) {
;                 const int r = uu.pm * 256 + (t2 & 255);
.LBB0_970:
	s_or_b64 exec, exec, s[0:1]
	s_and_b64 vcc, exec, s[38:39]
	s_movk_i32 s26, 0x82
	s_waitcnt lgkmcnt(0)
	s_barrier
	s_cbranch_vccnz .LBB0_972
	v_mov_b32_e32 v59, v0
	s_mul_i32 s13, s84, 0xa00
	v_readfirstlane_b32 s14, v59
	s_ashr_i32 s15, s14, 6
	s_mul_hi_i32 s14, s84, 0xa00
	s_add_u32 s18, s82, s13
	s_addc_u32 s13, s83, s14
	s_lshl_b32 s20, s15, 5
	s_ashr_i32 s21, s20, 31
	s_lshl_b64 s[24:25], s[20:21], 1
	s_add_u32 s20, s18, s24
	s_addc_u32 s21, s13, s25
	v_readlane_b32 s13, v254, 17
	v_readlane_b32 s14, v254, 18
	s_add_u32 s18, s13, s24
	s_addc_u32 s19, s14, s25
	v_and_b32_e32 v76, 48, v59
	v_mov_b32_e32 v77, 0
	v_lshl_add_u64 v[78:79], s[18:19], 0, v[76:77]
	s_lshr_b32 s13, s23, 1
	v_and_b32_e32 v80, 15, v59
	s_and_b32 s14, s13, 0x60
	s_and_b32 s13, s23, 0x300
	v_mul_u32_u24_e32 v81, 0x500, v80
	s_or_b32 s18, s13, s14
	v_or_b32_e32 v82, s18, v80
	v_lshlrev_b32_e32 v84, 1, v81
	v_mov_b32_e32 v85, v77
	s_movk_i32 s13, 0xa00
	v_mov_b32_e32 v80, 0x5a000
	v_mul_u32_u24_e32 v86, 0xa00, v82
	v_mov_b32_e32 v87, v77
	v_lshl_add_u64 v[88:89], s[20:21], 0, v[84:85]
	v_mov_b32_e32 v91, v77
	v_mad_u32_u24 v90, v82, s13, v80
	v_lshl_add_u64 v[80:81], v[78:79], 0, v[86:87]
	v_lshl_add_u64 v[86:87], v[88:89], 0, v[76:77]
	s_mov_b32 s14, 0xa000
	v_lshl_add_u64 v[88:89], v[78:79], 0, v[90:91]
	global_load_dwordx4 v[92:95], v[86:87], off offset:2048
	global_load_dwordx4 v[96:99], v[80:81], off
	s_mov_b32 s18, 0x50000
	global_load_dwordx4 v[100:103], v[88:89], off
	v_add_co_u32_e32 v78, vcc, s14, v86
	s_nop 1
	s_mul_hi_i32 s19, s15, 0xc0
	v_addc_co_u32_e32 v79, vcc, 0, v87, vcc
	s_nop 1
	v_add_co_u32_e32 v86, vcc, s14, v80
	s_nop 1
	global_load_dwordx4 v[88:91], v[78:79], off offset:2048
	v_addc_co_u32_e32 v87, vcc, 0, v81, vcc
	s_nop 1
	v_add_co_u32_e32 v78, vcc, s18, v80
	s_nop 1
	global_load_dwordx4 v[104:107], v[86:87], off
	v_addc_co_u32_e32 v79, vcc, 0, v81, vcc
	s_nop 1
	global_load_dwordx4 v[108:111], v[78:79], off
	s_mul_i32 s24, s15, 0xc0
	s_lshl_b32 s28, s15, 7
	s_ashr_i32 s29, s28, 31
	s_add_u32 s30, s20, s24
	s_addc_u32 s31, s21, s19
	s_lshl_b64 s[20:21], s[28:29], 1
	s_add_u32 s24, s86, s20
	v_mul_u32_u24_e32 v78, 0x500, v82
	s_addc_u32 s25, s87, s21
	v_mov_b32_e32 v81, v77
	v_lshlrev_b32_e32 v80, 1, v78
	v_lshl_add_u64 v[78:79], s[24:25], 0, v[76:77]
	v_lshl_add_u64 v[82:83], v[78:79], 0, v[80:81]
	v_add_co_u32_e32 v86, vcc, s14, v82
	s_nop 1
	v_addc_co_u32_e32 v87, vcc, 0, v83, vcc
	s_nop 1
	v_lshl_add_u64 v[112:113], s[30:31], 0, v[84:85]
	v_add_co_u32_e32 v84, vcc, s18, v82
	s_nop 1
	v_add_u32_e32 v116, 0x5a000, v80
	v_lshl_add_u64 v[118:119], v[112:113], 0, v[76:77]
	v_addc_co_u32_e32 v85, vcc, 0, v83, vcc
	s_nop 1
	v_mov_b32_e32 v112, v116
	v_mov_b32_e32 v113, v81
	v_lshl_add_u64 v[120:121], v[78:79], 0, v[112:113]
	v_add_co_u32_e32 v78, vcc, s14, v118
	s_nop 1
	s_mov_b64 s[14:15], 0xa000
	v_addc_co_u32_e32 v79, vcc, 0, v119, vcc
	s_nop 1
	v_lshl_add_u64 v[80:81], v[82:83], 0, s[14:15]
	s_mov_b64 s[14:15], 0x50000
	v_lshl_add_u64 v[112:113], v[82:83], 0, s[14:15]
	v_ashrrev_i32_e32 v76, 4, v59
	v_lshlrev_b32_e32 v116, 2, v59
	v_and_or_b32 v59, v116, 60, s22
	s_movk_i32 s14, 0x80
	global_load_dwordx4 v[124:127], v[118:119], off
	global_load_dwordx4 v[128:131], v[82:83], off
	global_load_dwordx4 v[132:135], v[86:87], off
	global_load_dwordx4 v[136:139], v[84:85], off
	global_load_dwordx4 v[84:87], v[118:119], off offset:64
	global_load_dwordx4 v[140:143], v[82:83], off offset:64
	global_load_dwordx4 v[144:147], v[120:121], off
	global_load_dwordx4 v[148:151], v[120:121], off offset:64
	global_load_dwordx4 v[152:155], v[78:79], off
	global_load_dwordx4 v[156:159], v[78:79], off offset:64
	global_load_dwordx4 v[160:163], v[80:81], off offset:128
	global_load_dwordx4 v[164:167], v[80:81], off offset:64
	global_load_dwordx4 v[168:171], v[112:113], off offset:64
	global_load_dwordx4 v[172:175], v[80:81], off offset:192
	global_load_dwordx4 v[176:179], v[82:83], off offset:128
	global_load_dwordx4 v[180:183], v[112:113], off offset:128
	global_load_dwordx4 v[184:187], v[118:119], off offset:128
	global_load_dwordx4 v[188:191], v[120:121], off offset:128
	global_load_dwordx4 v[192:195], v[118:119], off offset:192
	global_load_dwordx4 v[116:119], v[82:83], off offset:192
	global_load_dwordx4 v[80:83], v[112:113], off offset:192
	global_load_dwordx4 v[196:199], v[78:79], off offset:128
	global_load_dwordx4 v[200:203], v[120:121], off offset:192
	global_load_dwordx4 v[120:123], v[78:79], off offset:192
	v_add_u32_e32 v78, s84, v76
	v_ashrrev_i32_e32 v79, 31, v78
	v_lshlrev_b64 v[112:113], 6, v[78:79]
	v_lshl_add_u64 v[204:205], s[8:9], 0, v[112:113]
	v_lshlrev_b32_e32 v76, 1, v59
	global_load_dwordx4 v[208:211], v[204:205], off
	global_load_dwordx4 v[212:215], v[204:205], off offset:16
	global_load_dwordx4 v[216:219], v[204:205], off offset:32
	global_load_dwordx4 v[220:223], v[204:205], off offset:48
	v_mov_b64_e32 v[112:113], s[82:83]
	v_mad_i64_i32 v[204:205], s[18:19], v78, s13, v[112:113]
	v_mov_b32_e32 v78, v76
	v_mov_b32_e32 v79, v77
	v_lshl_add_u64 v[112:113], v[204:205], 0, v[78:79]
	global_load_dwordx2 v[76:77], v[112:113], off
	v_mov_b32_e32 v59, v0
	v_ashrrev_i32_e32 v78, 8, v59
	v_ashrrev_i32_e32 v79, 31, v78
	v_lshlrev_b64 v[112:113], 8, v[78:79]
	v_lshl_add_u64 v[78:79], v[112:113], 0, s[94:95]
	v_ashrrev_i32_e32 v79, 31, v78
	v_lshrrev_b32_e32 v112, 29, v79
	v_add_u32_e32 v79, v78, v112
	v_ashrrev_i32_e32 v112, 3, v79
	v_and_b32_e32 v204, -8, v79
	v_sub_u32_e32 v79, v78, v204
	s_lshr_b32 s13, s14, 1
	v_lshrrev_b32_e32 v78, 31, v79
	v_add_u32_e32 v204, s13, v78
	v_mov_b32_e32 v113, 0
	v_mad_u64_u32 v[206:207], s[18:19], v204, v79, v[112:113]
;     __device__ bool next(int i, Unit& u) const {
;         const int it = (nseg == 2) ? (i >> 1) : i;
;         const long L = (long)it * G + c; if (L >= nwg) return false;
;         int wgid = (int)L; { const int q = nwg / NXCD, r = nwg % NXCD, xcd = wgid % NXCD, off = wgid / NXCD; wgid = (xcd < r ? xcd * (q + 1) : r * (q + 1) + (xcd - r) * q) + off; }
;         const int nig = WGM * nN, gid = wgid / nig, fm = gid * WGM, gsz = (nM - fm) < WGM ? (nM - fm) : WGM;
;         u.pm = fm + ((wgid % nig) % gsz); u.pn = (wgid % nig) / gsz; u.seg = (nseg == 2) ? (i & 1) : 0; u.ti = it; return true;
; __global__ void __launch_bounds__(NWAVES * 64, 2) fwd_megakernel(Args args) {
;     ...
;             tail_partial<1>(HP + (size_t)row0 * LDHP + 1024 + wave * 32, LDHP, WGP_t + 1024 + wave * 32, LDHP, col0, parts + wave * 2048, lane);
;             __syncthreads();
;             const f32x4 ple = tail_sum(parts, 0, 8, tid);
;             __syncthreads();
;             tail_partial<4>(HP + (size_t)row0 * LDHP + wave * 128, LDHP, WGP_t + wave * 128, LDHP, col0, parts + wave * 2048, lane);
;             __syncthreads();
;             const f32x4 cc = tail_sum(parts, 0, 8, tid);
	v_ashrrev_i32_e32 v78, 31, v206
	v_lshrrev_b32_e32 v79, 27, v78
	v_add_u32_e32 v78, v206, v79
	v_ashrrev_i32_e32 v79, 5, v78
	v_lshlrev_b32_e32 v112, 3, v79
	v_sub_u32_e32 v79, s14, v112
	v_min_i32_e32 v113, 8, v79
	v_sub_u32_e32 v79, 0, v113
	v_max_i32_e32 v204, v113, v79
	v_cvt_f32_u32_e32 v79, v204
	v_and_b32_e32 v113, 0xffffffe0, v78
	v_sub_u32_e32 v78, v206, v113
	v_sub_u32_e32 v113, 0, v78
	v_rcp_iflag_f32_e32 v205, v79
	s_nop 0
	v_ashrrev_i32_e32 v79, 31, v78
	v_max_i32_e32 v206, v78, v113
	v_sub_u32_e32 v78, 0, v204
	v_mul_f32_e32 v113, 0x4f7ffffe, v205
	v_cvt_u32_f32_e32 v205, v113
	s_mov_b32 s13, 0x6050400
	v_mul_lo_u32 v113, v78, v205
	v_mul_hi_u32 v78, v205, v113
	v_add_u32_e32 v113, v205, v78
	v_mul_hi_u32 v78, v206, v113
	v_mul_lo_u32 v113, v78, v204
	v_sub_u32_e32 v78, v206, v113
	v_sub_u32_e32 v113, v78, v204
	v_cmp_ge_u32_e32 vcc, v78, v204
	s_nop 1
	v_cndmask_b32_e32 v205, v78, v113, vcc
	v_sub_u32_e32 v78, v205, v204
	v_cmp_ge_u32_e32 vcc, v205, v204
	s_nop 1
	v_cndmask_b32_e32 v113, v205, v78, vcc
	v_xor_b32_e32 v78, v113, v79
	v_sub_u32_e32 v113, v78, v79
	v_add_u32_e32 v78, v113, v112
	v_perm_b32 v112, v78, v59, s13
	v_ashrrev_i32_e32 v113, 31, v112
	v_lshlrev_b64 v[78:79], 6, v[112:113]
	v_lshl_add_u64 v[112:113], s[8:9], 0, v[78:79]
	global_load_dwordx4 v[204:207], v[112:113], off
	global_load_dwordx4 v[224:227], v[112:113], off offset:16
	global_load_dwordx4 v[228:231], v[112:113], off offset:32
	global_load_dwordx4 v[232:235], v[112:113], off offset:48
	v_mov_b32_e32 v1, v0
	s_nop 0
	v_readfirstlane_b32 s0, v1
	s_ashr_i32 s4, s0, 6
	s_nop 0
	s_nop 0
	s_nop 0
	s_nop 0
	s_nop 0
	s_nop 0
	s_nop 0
	s_nop 0
	s_nop 0
	s_nop 0
	s_nop 0
	s_nop 0
	v_and_b32_e32 v34, 48, v1
	v_mov_b32_e32 v35, 0
	s_nop 0
	s_nop 0
	v_and_b32_e32 v36, 15, v1
	s_nop 0
	s_nop 0
	s_nop 0
	s_nop 0
	s_nop 0
	s_nop 0
	s_nop 0
	s_nop 0
	s_nop 0
	s_nop 0
	s_nop 0
	s_nop 0
	s_nop 0
	s_nop 0
	s_nop 0
	s_nop 0
	s_nop 0
	s_nop 0
	s_nop 0
	s_nop 0
	s_nop 0
	s_nop 0
	s_nop 0
	s_nop 0
	s_nop 0
	s_nop 0
	s_nop 0
	s_nop 0
	s_nop 0
	s_nop 0
	s_nop 0
	s_nop 0
	s_nop 0
	s_nop 0
	s_nop 0
	s_nop 0
	s_lshl_b32 s5, s4, 13
	s_nop 0
	s_add_i32 s11, s5, 0
	s_nop 0
	s_nop 0
	s_nop 0
	s_nop 0
	s_nop 0
	s_nop 0
	s_nop 0
	s_nop 0
	s_nop 0
	s_nop 0
	s_nop 0
	s_nop 0
	v_lshlrev_b32_e32 v36, 8, v36
	s_nop 0
	s_nop 0
	s_nop 0
	s_nop 0
	s_nop 0
	v_lshl_add_u32 v114, v1, 4, 0
	v_add3_u32 v115, s11, v36, v34
	s_nop 0
	s_nop 0
	s_nop 0
	s_nop 0
	s_nop 0
	s_nop 0
	s_nop 0
	s_nop 0
	s_nop 0
	s_nop 0
	v_ashrrev_i32_e32 v34, 4, v1
	v_lshlrev_b32_e32 v1, 2, v1
	v_and_or_b32 v1, v1, 60, s22
	s_nop 0
	s_waitcnt vmcnt(37)
	v_mfma_f32_16x16x32_bf16 v[22:25], v[96:99], v[92:95], 0
	s_movk_i32 s26, 0x80
	s_nop 0
	s_waitcnt vmcnt(36)
	v_mfma_f32_16x16x32_bf16 v[30:33], v[100:103], v[92:95], 0
	s_nop 0
	s_waitcnt vmcnt(35)
	v_mfma_f32_16x16x32_bf16 v[2:5], v[96:99], v[88:91], 0
	v_mfma_f32_16x16x32_bf16 v[10:13], v[100:103], v[88:91], 0
	s_nop 0
	s_waitcnt vmcnt(34)
	v_mfma_f32_16x16x32_bf16 v[36:39], v[104:107], v[92:95], 0
	s_nop 0
	s_waitcnt vmcnt(33)
	v_mfma_f32_16x16x32_bf16 v[6:9], v[108:111], v[92:95], 0
	v_mfma_f32_16x16x32_bf16 v[18:21], v[104:107], v[88:91], 0
	v_mfma_f32_16x16x32_bf16 v[14:17], v[108:111], v[88:91], 0
	ds_write_b128 v115, v[22:25]
	ds_write_b128 v115, v[30:33] offset:192
	ds_write_b128 v115, v[2:5] offset:4096
	ds_write_b128 v115, v[10:13] offset:4288
	ds_write_b128 v115, v[36:39] offset:64
	s_nop 0
	ds_write_b128 v115, v[6:9] offset:128
	ds_write_b128 v115, v[18:21] offset:4160
	ds_write_b128 v115, v[14:17] offset:4224
	s_waitcnt lgkmcnt(0)
	s_barrier
	ds_read_b128 v[30:33], v114
	ds_read_b128 v[26:29], v114 offset:8192
	ds_read_b128 v[22:25], v114 offset:16384
	ds_read_b128 v[18:21], v114 offset:24576
	ds_read_b128 v[14:17], v114 offset:32768
	ds_read_b128 v[10:13], v114 offset:40960
	ds_read_b128 v[6:9], v114 offset:49152
	ds_read_b128 v[2:5], v114 offset:57344
	s_waitcnt lgkmcnt(0)
	s_barrier
	s_nop 0
	s_nop 0
	v_pk_add_f32 v[32:33], v[32:33], 0 op_sel_hi:[1,0]
	s_nop 0
	s_nop 0
	s_nop 0
	s_nop 0
	s_nop 0
	s_nop 0
	s_nop 0
	s_nop 0
	s_nop 0
	v_pk_add_f32 v[30:31], v[30:31], 0 op_sel_hi:[1,0]
	v_pk_add_f32 v[28:29], v[32:33], v[28:29]
	v_pk_add_f32 v[26:27], v[30:31], v[26:27]
	v_pk_add_f32 v[24:25], v[28:29], v[24:25]
	v_pk_add_f32 v[22:23], v[26:27], v[22:23]
	v_pk_add_f32 v[20:21], v[24:25], v[20:21]
	v_pk_add_f32 v[18:19], v[22:23], v[18:19]
	v_pk_add_f32 v[16:17], v[20:21], v[16:17]
	v_pk_add_f32 v[14:15], v[18:19], v[14:15]
	v_pk_add_f32 v[12:13], v[16:17], v[12:13]
	v_pk_add_f32 v[10:11], v[14:15], v[10:11]
	v_pk_add_f32 v[8:9], v[12:13], v[8:9]
	v_pk_add_f32 v[6:7], v[10:11], v[6:7]
	s_nop 0
	s_waitcnt vmcnt(29)
	v_mfma_f32_16x16x32_bf16 v[72:75], v[136:139], v[124:127], 0
	s_nop 0
	v_mfma_f32_16x16x32_bf16 v[60:63], v[128:131], v[124:127], 0
	v_mfma_f32_16x16x32_bf16 v[64:67], v[132:135], v[124:127], 0
	s_nop 0
	s_waitcnt vmcnt(26)
	v_mfma_f32_16x16x32_bf16 v[36:39], v[144:147], v[124:127], 0
	s_nop 0
	s_waitcnt vmcnt(24)
	v_mfma_f32_16x16x32_bf16 v[40:43], v[128:131], v[152:155], 0
	v_mfma_f32_16x16x32_bf16 v[44:47], v[132:135], v[152:155], 0
	v_mfma_f32_16x16x32_bf16 v[48:51], v[136:139], v[152:155], 0
	v_mfma_f32_16x16x32_bf16 v[68:71], v[144:147], v[152:155], 0
	s_nop 0
	s_nop 0
	s_nop 0
	v_mfma_f32_16x16x32_bf16 v[60:63], v[140:143], v[84:87], v[60:63]
	s_nop 0
	s_waitcnt vmcnt(21)
	v_mfma_f32_16x16x32_bf16 v[64:67], v[164:167], v[84:87], v[64:67]
	s_nop 0
	s_waitcnt vmcnt(20)
; #define LAS __attribute__((address_space(3)))
; template <int KSTEPS>
; __device__ __forceinline__ void tail_partial(const bf16_t* A, int lda, const bf16_t* Bt, int ldb, int col0, LAS float* part, int lane) {
;     ...
;     for (int ks = 0; ks < KSTEPS; ++ks) {
;         bf16x8 a[2], b[4];
; #pragma unroll
;         for (int m = 0; m < 2; ++m) a[m] = *(const bf16x8*)(ap + (size_t)(16 * m) * lda + 32 * ks);
; #pragma unroll
;         for (int n = 0; n < 4; ++n) b[n] = *(const bf16x8*)(bp[n] + 32 * ks);
; #pragma unroll
;         for (int m = 0; m < 2; ++m)
; #pragma unroll
;             for (int n = 0; n < 4; ++n) acc[m][n] = __builtin_amdgcn_mfma_f32_16x16x32_bf16(b[n], a[m], acc[m][n], 0, 0, 0);
;     }
; #pragma unroll
;     for (int m = 0; m < 2; ++m)
; #pragma unroll
;         for (int n = 0; n < 4; ++n) *(LAS f32x4*)(part + (16 * m + fr) * 64 + 16 * n + 4 * fq) = acc[m][n];
	v_mfma_f32_16x16x32_bf16 v[72:75], v[168:171], v[84:87], v[72:75]
	v_mfma_f32_16x16x32_bf16 v[36:39], v[148:151], v[84:87], v[36:39]
	s_nop 0
	v_mfma_f32_16x16x32_bf16 v[44:47], v[164:167], v[156:159], v[44:47]
	s_nop 0
	v_mfma_f32_16x16x32_bf16 v[40:43], v[140:143], v[156:159], v[40:43]
	s_nop 0
	v_mfma_f32_16x16x32_bf16 v[48:51], v[168:171], v[156:159], v[48:51]
	v_mfma_f32_16x16x32_bf16 v[68:71], v[148:151], v[156:159], v[68:71]
	s_nop 0
	s_nop 0
	s_nop 0
	s_nop 0
	s_nop 0
	s_nop 0
	s_waitcnt vmcnt(16)
	v_mfma_f32_16x16x32_bf16 v[60:63], v[176:179], v[184:187], v[60:63]
	s_nop 0
	s_nop 0
	s_nop 0
	v_mfma_f32_16x16x32_bf16 v[64:67], v[160:163], v[184:187], v[64:67]
	v_mfma_f32_16x16x32_bf16 v[72:75], v[180:183], v[184:187], v[72:75]
	s_nop 0
	s_waitcnt vmcnt(15)
	v_mfma_f32_16x16x32_bf16 v[36:39], v[188:191], v[184:187], v[36:39]
	s_nop 0
	s_nop 0
	s_waitcnt vmcnt(11)
	v_mfma_f32_16x16x32_bf16 v[40:43], v[176:179], v[196:199], v[40:43]
	v_mfma_f32_16x16x32_bf16 v[44:47], v[160:163], v[196:199], v[44:47]
	v_mfma_f32_16x16x32_bf16 v[48:51], v[180:183], v[196:199], v[48:51]
	v_mfma_f32_16x16x32_bf16 v[52:55], v[188:191], v[196:199], v[68:71]
	v_mfma_f32_16x16x32_bf16 v[60:63], v[116:119], v[192:195], v[60:63]
	v_mfma_f32_16x16x32_bf16 v[68:71], v[80:83], v[192:195], v[72:75]
	s_nop 2
	v_add_u32_e32 v72, s84, v34
	v_mfma_f32_16x16x32_bf16 v[64:67], v[172:175], v[192:195], v[64:67]
	v_ashrrev_i32_e32 v73, 31, v72
	s_nop 0
	s_nop 0
	s_nop 0
	s_waitcnt vmcnt(10)
	v_mfma_f32_16x16x32_bf16 v[36:39], v[200:203], v[192:195], v[36:39]
	s_nop 0
	s_nop 0
	s_waitcnt vmcnt(9)
	v_mfma_f32_16x16x32_bf16 v[40:43], v[116:119], v[120:123], v[40:43]
	v_mfma_f32_16x16x32_bf16 v[44:47], v[172:175], v[120:123], v[44:47]
	v_mfma_f32_16x16x32_bf16 v[48:51], v[80:83], v[120:123], v[48:51]
	v_mfma_f32_16x16x32_bf16 v[52:55], v[200:203], v[120:123], v[52:55]
	ds_write_b128 v115, v[60:63]
	ds_write_b128 v115, v[64:67] offset:64
	ds_write_b128 v115, v[68:71] offset:128
	ds_write_b128 v115, v[36:39] offset:192
	s_nop 0
	ds_write_b128 v115, v[40:43] offset:4096
	ds_write_b128 v115, v[44:47] offset:4160
	ds_write_b128 v115, v[48:51] offset:4224
	ds_write_b128 v115, v[52:55] offset:4288
	s_waitcnt lgkmcnt(0)
	s_barrier
; #define LAS __attribute__((address_space(3)))
; __device__ __forceinline__ float bf_lo(unsigned w) { return __uint_as_float(w << 16); }
; __device__ __forceinline__ float bf_hi(unsigned w) { return __uint_as_float(w & 0xffff0000u); }
; __device__ __forceinline__ float sigmoidf_(float x) { return fast_rcp(1.f + fast_exp2(-LOG2E * x)); }
; __device__ __forceinline__ int fresh_tid() { int t = threadIdx.x; asm volatile("" : "+v"(t)); return t; }
; __global__ void __launch_bounds__(NWAVES * 64, 2) fwd_megakernel(Args args) {
;     ...
;             const f32x4 cc = tail_sum(parts, 0, 8, tid);
;             const int r = row0 + (tid >> 4), c = col0 + (tid & 15) * 4;
;             const f32x4* sp = (const f32x4*)(SS + (size_t)r * 16);
;             const f32x4 s0 = sp[0], s1 = sp[1], s2 = sp[2], s3 = sp[3];
;             const float st = ((s0[0] + s0[1]) + (s0[2] + s0[3])) + ((s1[0] + s1[1]) + (s1[2] + s1[3])) + ((s2[0] + s2[1]) + (s2[2] + s2[3])) + ((s3[0] + s3[1]) + (s3[2] + s3[3]));
;             const float rstd = rsqrtf(st * (1.f / DM) + EPS);
;             const u32x2 hw = *(const u32x2*)(HP + (size_t)r * LDHP + c);
;             f32x4 y;
;             y[0] = bf_lo(hw.x) + sigmoidf_(rstd * cc[0]) * ple[0]; y[1] = bf_hi(hw.x) + sigmoidf_(rstd * cc[1]) * ple[1];
;             y[2] = bf_lo(hw.y) + sigmoidf_(rstd * cc[2]) * ple[2]; y[3] = bf_hi(hw.y) + sigmoidf_(rstd * cc[3]) * ple[3];
;             *(f32x4*)(out + (size_t)r * DM + c) = y;
;             __syncthreads();
;         }
;         pg8::Gemm g{HP, WGP_t, LDHP, LDHP};
;         pg8::StaticOrder S; S.init(G == 256 ? MP : M, DM, G, bx, 2);
;         LAS float* rs = nullptr;
;         if (G == 256) {
;             const int t2 = fresh_tid();
;             rs = (LAS float*)(lds + TBL_OFF);
;             pg8::Unit uu; if (S.next(2 * (t2 >> 8), uu)) {
;                 const int r = uu.pm * 256 + (t2 & 255);
;                 const f32x4* sp = (const f32x4*)(SS + (size_t)r * 16); const f32x4 s0 = sp[0], s1 = sp[1], s2 = sp[2], s3 = sp[3];
;                 const float st = ((s0[0] + s0[1]) + (s0[2] + s0[3])) + ((s1[0] + s1[1]) + (s1[2] + s1[3])) + ((s2[0] + s2[1]) + (s2[2] + s2[3])) + ((s3[0] + s3[1]) + (s3[2] + s3[3]));
;                 rs[t2] = rsqrtf(st * (1.f / DM) + EPS); }
;             __syncthreads();
	s_nop 0
	s_nop 0
	s_nop 0
	s_nop 0
	s_nop 0
	s_nop 0
	s_nop 0
	s_nop 0
	v_lshlrev_b64 v[54:55], 12, v[72:73]
	v_lshl_add_u64 v[54:55], s[60:61], 0, v[54:55]
	v_lshlrev_b32_e32 v34, 2, v1
	v_lshl_add_u64 v[34:35], v[54:55], 0, v[34:35]
	v_pk_add_f32 v[54:55], v[8:9], v[4:5]
	v_pk_add_f32 v[56:57], v[6:7], v[2:3]
	ds_read_b128 v[2:5], v114
	ds_read_b128 v[6:9], v114 offset:8192
	ds_read_b128 v[10:13], v114 offset:16384
	ds_read_b128 v[14:17], v114 offset:24576
	ds_read_b128 v[18:21], v114 offset:32768
	ds_read_b128 v[22:25], v114 offset:40960
	ds_read_b128 v[26:29], v114 offset:49152
	ds_read_b128 v[30:33], v114 offset:57344
	s_waitcnt lgkmcnt(7)
	v_pk_add_f32 v[4:5], v[4:5], 0 op_sel_hi:[1,0]
	v_pk_add_f32 v[2:3], v[2:3], 0 op_sel_hi:[1,0]
	s_waitcnt lgkmcnt(6)
	v_pk_add_f32 v[4:5], v[4:5], v[8:9]
	v_pk_add_f32 v[2:3], v[2:3], v[6:7]
	s_waitcnt lgkmcnt(5)
	v_pk_add_f32 v[4:5], v[4:5], v[12:13]
	v_pk_add_f32 v[2:3], v[2:3], v[10:11]
	v_mov_b32_e32 v58, 0x358637bd
	s_mov_b32 s0, 0x800000
	s_waitcnt lgkmcnt(4)
	v_pk_add_f32 v[4:5], v[4:5], v[16:17]
	v_pk_add_f32 v[2:3], v[2:3], v[14:15]
	s_waitcnt lgkmcnt(3)
	v_pk_add_f32 v[4:5], v[4:5], v[20:21]
	v_pk_add_f32 v[2:3], v[2:3], v[18:19]
	s_waitcnt lgkmcnt(2)
	v_pk_add_f32 v[4:5], v[4:5], v[24:25]
	v_pk_add_f32 v[2:3], v[2:3], v[22:23]
	s_waitcnt lgkmcnt(1)
	v_pk_add_f32 v[4:5], v[4:5], v[28:29]
	v_pk_add_f32 v[2:3], v[2:3], v[26:27]
	s_waitcnt lgkmcnt(0)
	v_pk_add_f32 v[4:5], v[4:5], v[32:33]
	v_pk_add_f32 v[2:3], v[2:3], v[30:31]
	s_nop 0
	s_waitcnt vmcnt(8)
	v_mov_b32_e32 v6, v209
	v_mov_b32_e32 v7, v210
	v_mov_b32_e32 v37, v211
	s_nop 0
	s_waitcnt vmcnt(7)
	v_mov_b32_e32 v8, v213
	v_mov_b32_e32 v9, v214
	v_mov_b32_e32 v41, v215
	v_mov_b32_e32 v36, v208
	v_pk_add_f32 v[6:7], v[6:7], v[36:37]
	v_mov_b32_e32 v40, v212
	v_pk_add_f32 v[8:9], v[8:9], v[40:41]
	v_pk_add_f32 v[6:7], v[6:7], v[6:7] op_sel:[0,1] op_sel_hi:[1,0]
	v_pk_add_f32 v[8:9], v[8:9], v[8:9] op_sel:[0,1] op_sel_hi:[1,0]
	s_nop 0
	s_waitcnt vmcnt(6)
	v_add_f32_e32 v10, v216, v217
	v_add_f32_e32 v12, v218, v219
	s_nop 0
	s_waitcnt vmcnt(5)
	v_mov_b32_e32 v11, v222
	v_mov_b32_e32 v13, v223
	v_mov_b32_e32 v7, v220
	v_mov_b32_e32 v9, v221
	v_pk_add_f32 v[10:11], v[10:11], v[12:13]
	v_pk_add_f32 v[6:7], v[6:7], v[8:9]
	s_nop 0
	s_waitcnt vmcnt(4)
	v_and_b32_e32 v9, 0xffff0000, v77
	v_pk_add_f32 v[6:7], v[6:7], v[10:11]
	s_nop 0
	v_add_f32_e32 v1, v6, v7
	v_fmac_f32_e32 v58, 0x3a800000, v1
	v_mul_f32_e32 v1, 0x4b800000, v58
	v_cmp_gt_f32_e32 vcc, s0, v58
	v_lshlrev_b32_e32 v6, 16, v76
	v_and_b32_e32 v7, 0xffff0000, v76
	v_cndmask_b32_e32 v1, v58, v1, vcc
	v_rsq_f32_e32 v1, v1
	s_nop 0
	v_mul_f32_e32 v8, 0x45800000, v1
	v_cndmask_b32_e32 v1, v1, v8, vcc
	v_mul_f32_e32 v2, v2, v1
	v_mul_f32_e32 v3, v3, v1
	v_mul_f32_e32 v4, v4, v1
	v_mul_f32_e32 v1, v5, v1
	v_mul_f32_e32 v2, 0xbfb8aa3b, v2
	v_mul_f32_e32 v3, 0xbfb8aa3b, v3
	v_mul_f32_e32 v4, 0xbfb8aa3b, v4
	v_mul_f32_e32 v1, 0xbfb8aa3b, v1
	v_exp_f32_e32 v2, v2
	v_exp_f32_e32 v3, v3
	v_exp_f32_e32 v4, v4
	v_exp_f32_e32 v1, v1
	v_add_f32_e32 v2, 1.0, v2
	v_add_f32_e32 v3, 1.0, v3
	v_add_f32_e32 v4, 1.0, v4
	v_add_f32_e32 v1, 1.0, v1
	v_rcp_f32_e32 v2, v2
	v_rcp_f32_e32 v3, v3
	v_rcp_f32_e32 v4, v4
	v_rcp_f32_e32 v5, v1
	v_lshlrev_b32_e32 v8, 16, v77
	v_pk_fma_f32 v[2:3], v[56:57], v[2:3], v[6:7]
	v_pk_fma_f32 v[4:5], v[54:55], v[4:5], v[8:9]
	global_store_dwordx4 v[34:35], v[2:5], off
	s_barrier
	s_lshl_b32 s16, s26, 2
	s_nop 0
	v_mov_b32_e32 v1, v0
	s_mov_b32 s17, 0
	v_ashrrev_i32_e32 v2, 8, v1
	v_ashrrev_i32_e32 v3, 31, v2
	v_lshlrev_b64 v[2:3], 8, v[2:3]
	v_lshl_add_u64 v[2:3], v[2:3], 0, s[94:95]
	v_cmp_gt_i64_e32 vcc, s[16:17], v[2:3]
	s_and_saveexec_b64 s[0:1], vcc
	s_nop 0
	s_nop 0
	s_nop 0
	s_nop 0
	s_nop 0
	s_nop 0
	s_nop 0
	s_nop 0
	s_nop 0
	s_nop 0
	s_nop 0
	s_nop 0
	s_nop 0
	s_nop 0
	s_nop 0
	s_nop 0
	s_nop 0
	s_nop 0
	s_nop 0
	s_nop 0
	s_nop 0
	s_nop 0
	s_nop 0
	s_nop 0
	s_nop 0
	s_nop 0
	s_nop 0
	s_nop 0
	s_nop 0
	s_nop 0
	s_nop 0
	v_mov_b32_e32 v20, 0x358637bd
	s_nop 0
	s_nop 0
	s_nop 0
	s_nop 0
	s_nop 0
	s_nop 0
	s_nop 0
	s_nop 0
	s_nop 1
	s_nop 0
	s_nop 0
	s_nop 0
	s_nop 1
	s_nop 0
	s_nop 0
	s_nop 0
	s_nop 0
	s_nop 0
	s_nop 0
	s_nop 0
	s_nop 0
	s_nop 0
	s_nop 0
	s_nop 0
	s_nop 0
	s_mov_b32 s2, 0x800000
	v_lshl_add_u32 v1, v1, 2, 0
	v_add_u32_e32 v1, 0x20200, v1
	s_nop 0
	s_waitcnt vmcnt(4)
	v_mov_b32_e32 v18, v205
	v_mov_b32_e32 v19, v206
	v_mov_b32_e32 v3, v207
	s_nop 0
	s_waitcnt vmcnt(3)
	v_mov_b32_e32 v4, v225
	v_mov_b32_e32 v5, v226
	v_mov_b32_e32 v7, v227
	v_mov_b32_e32 v2, v204
	v_pk_add_f32 v[2:3], v[18:19], v[2:3]
	v_mov_b32_e32 v6, v224
	v_pk_add_f32 v[4:5], v[4:5], v[6:7]
	v_pk_add_f32 v[2:3], v[2:3], v[2:3] op_sel:[0,1] op_sel_hi:[1,0]
	v_pk_add_f32 v[4:5], v[4:5], v[4:5] op_sel:[0,1] op_sel_hi:[1,0]
	s_nop 0
	s_waitcnt vmcnt(2)
	v_add_f32_e32 v8, v228, v229
	v_add_f32_e32 v10, v230, v231
	s_nop 0
	s_waitcnt vmcnt(1)
	v_mov_b32_e32 v9, v234
	v_mov_b32_e32 v11, v235
	v_mov_b32_e32 v3, v232
	v_mov_b32_e32 v5, v233
	v_pk_add_f32 v[6:7], v[8:9], v[10:11]
	v_pk_add_f32 v[2:3], v[2:3], v[4:5]
	s_nop 0
	v_pk_add_f32 v[2:3], v[2:3], v[6:7]
	s_nop 0
	v_add_f32_e32 v2, v2, v3
	v_fmac_f32_e32 v20, 0x3a800000, v2
	v_mul_f32_e32 v2, 0x4b800000, v20
	v_cmp_gt_f32_e32 vcc, s2, v20
	s_nop 1
	v_cndmask_b32_e32 v2, v20, v2, vcc
	v_rsq_f32_e32 v2, v2
	s_nop 0
	v_mul_f32_e32 v3, 0x45800000, v2
	v_cndmask_b32_e32 v2, v2, v3, vcc
	ds_write_b32 v1, v2
	s_or_b64 exec, exec, s[0:1]
	s_add_i32 s12, 0, 0x20200
	s_waitcnt lgkmcnt(0)
	s_barrier
	s_branch .LBB0_976
